# barriers 1,2,3,5,6,7 replaced by per-batch 32-workgroup barriers (XCD-local, no L2 writeback when co-located)
# speedup vs baseline: 1.0309x; 1.0309x over previous
; #define LAS __attribute__((address_space(3)))
; __device__ __forceinline__ unsigned xb_add(unsigned* p, unsigned v) { return __hip_atomic_fetch_add(p, v, __ATOMIC_RELAXED, __HIP_MEMORY_SCOPE_AGENT); }
; __device__ __forceinline__ unsigned xb_xcc_id() { return (unsigned)__builtin_amdgcn_s_getreg((3 << 11) | 20) & 0xFu; }
; __device__ __forceinline__ XcdBarrier xcd_barrier_post(unsigned* bar, volatile LAS unsigned* st) {
;     XcdBarrier b; b.bar = bar; b.x = xb_xcc_id(); b.st = st;
;     if (threadIdx.x == 0) (void)xb_add(&bar[XB_XCNT(b.x)], 1u);
;     return b;
; __global__ void __launch_bounds__(NWAVES * 64, 2) skel_fwd(Args args) {
;     ...
;     unsigned char* ws = args.ws;
;     F.ctl = (gu32*)(ws + WS_CTL);
;     F.x = args.in[0]; F.g_pre_mix = args.in[1]; F.w_in = args.in[2]; F.w_pa = args.in[15]; F.w_pb = args.in[16]; F.w_o = args.in[17];
;     F.g_post_mix = args.in[18]; F.g_pre_mlp = args.in[19]; F.w_up = args.in[20]; F.w_down = args.in[21]; F.g_post_mlp = args.in[22]; F.out = args.out;
;     F.w_if = args.in[11]; F.w_q_ml = args.in[8]; F.w_k_ml = args.in[9]; F.w_v_ml = args.in[10]; F.Wif_t = (bf16*)(ws + WS_WIF);
;     F.W1t = (bf16*)(ws + WS_W1); F.Wpa_t = (bf16*)(ws + WS_WPA); F.Wpb_t = (bf16*)(ws + WS_WPB); F.Wo_t = (bf16*)(ws + WS_WO); F.Wup_t = (bf16*)(ws + WS_WUP); F.Wdn_t = (bf16*)(ws + WS_WDN);
;     F.XN = (bf16*)args.out + (size_t)M * 1024; F.XS = (float*)(ws + WS_SMALL + 1024 * 1024);
;     F.PROJ = (bf16*)(ws + WS_PROJ); F.A_a = (bf16*)(ws + WS_A); F.A_b = F.A_a + 512;
;     F.MERGED = (bf16*)(ws + WS_R1); F.XN2 = (bf16*)(ws + WS_XN2); F.U = (bf16*)(ws + WS_U);
;     for (int u = F.tid; u < (LDS_BYTES - LDSCTL_OFF) / 4; u += NWAVES * 64) ((LAS unsigned*)(F.lds + LDSCTL_OFF))[u] = 0u;
;     __syncthreads();
;     XcdBarrier bar = xcd_barrier_post((unsigned*)(F.ctl + CW_BAR), F.MISC + 8);
.LBB0_3:
	s_or_b64 exec, exec, s[2:3]
	s_load_dwordx16 s[52:67], s[0:1], 0x0
	s_load_dwordx16 s[8:23], s[0:1], 0x40
	s_waitcnt lgkmcnt(0)
	s_barrier
	s_add_u32 s86, s88, 0x4000
	v_writelane_b32 v241, s8, 2
	s_addc_u32 s87, s89, 0
	v_cmp_eq_u32_e64 s[2:3], 0, v0
	v_writelane_b32 v241, s9, 3
	v_writelane_b32 v241, s10, 4
	v_writelane_b32 v241, s11, 5
	v_writelane_b32 v241, s12, 6
	v_writelane_b32 v241, s13, 7
	v_writelane_b32 v241, s14, 8
	v_writelane_b32 v241, s15, 9
	v_writelane_b32 v241, s16, 10
	v_writelane_b32 v241, s17, 11
	v_writelane_b32 v241, s18, 12
	v_writelane_b32 v241, s19, 13
	v_writelane_b32 v241, s20, 14
	v_writelane_b32 v241, s21, 15
	v_writelane_b32 v241, s22, 16
	v_writelane_b32 v241, s23, 17
	s_load_dwordx16 s[8:23], s[0:1], 0x80
	s_getreg_b32 s0, hwreg(HW_REG_XCC_ID, 0, 4)
	s_and_b32 s97, s0, 15
	s_waitcnt lgkmcnt(0)
	s_and_b32 s99, s96, 7
	s_lshl_b32 s101, s99, 6
	s_lshl_b32 s99, s99, 8
	s_add_i32 s99, s99, 0x40000
	s_lshl_b32 s100, s97, 2
	s_or_b32 s101, s101, s100
	s_add_i32 s101, s101, 0x41000
	v_writelane_b32 v241, s8, 18
	s_nop 1
	v_writelane_b32 v241, s9, 19
	v_writelane_b32 v241, s10, 20
	v_writelane_b32 v241, s11, 21
	v_writelane_b32 v241, s12, 22
	v_writelane_b32 v241, s13, 23
	v_writelane_b32 v241, s14, 24
	v_writelane_b32 v241, s15, 25
	v_writelane_b32 v241, s16, 26
	v_writelane_b32 v241, s17, 27
	v_writelane_b32 v241, s18, 28
	v_writelane_b32 v241, s19, 29
	v_writelane_b32 v241, s20, 30
	v_writelane_b32 v241, s21, 31
	v_writelane_b32 v241, s22, 32
	v_writelane_b32 v241, s23, 33
	s_mov_b64 s[0:1], exec
	v_writelane_b32 v241, s2, 34
	s_nop 1
	v_writelane_b32 v241, s3, 35
	s_and_b64 s[2:3], s[0:1], s[2:3]
	s_mov_b64 exec, s[2:3]
	s_cbranch_execz .LBB0_6
	s_mov_b64 s[2:3], exec
	v_mbcnt_lo_u32_b32 v1, s2, 0
	v_mbcnt_hi_u32_b32 v1, s3, v1
	v_cmp_eq_u32_e32 vcc, 0, v1
	s_and_b64 s[6:7], exec, vcc
	s_mov_b64 exec, s[6:7]
	s_cbranch_execz .LBB0_6
	s_lshl_b32 s5, s97, 8
	s_bcnt1_i32_b64 s2, s[2:3]
	v_mov_b32_e32 v1, s5
	v_mov_b32_e32 v2, s2
	global_atomic_add v1, v2, s[86:87] offset:1024
	v_mov_b32_e32 v3, s101
	v_mov_b32_e32 v4, 1
	global_atomic_add v3, v4, s[88:89]

;     __host__ __device__ bool next(int i, Unit& u) const {
;         const long L = (long)i * G + c; if (L >= nwg) return false;
;         int wgid = (int)L; { const int q = nwg / NXCD, r = nwg % NXCD, xcd = wgid % NXCD, off = wgid / NXCD; wgid = (xcd < r ? xcd * (q + 1) : r * (q + 1) + (xcd - r) * q) + off; }
;         const int nig = wgm * nN, gid = wgid / nig, fm = gid * wgm, gsz = (nM - fm) < wgm ? (nM - fm) : wgm;
;         u.pm = fm + ((wgid % nig) % gsz); u.pn = (wgid % nig) / gsz; return true;
; template <class Epi, class Sched, bool ALIGN_EPI = false, bool SP2 = false>
; __device__ __forceinline__ void gemm_phase(PG8_LAS unsigned char* lds, const Gemm g, const Sched& S, const Epi& E) {
;     ...
;     if (!S.next(0, cur)) return;
.LBB0_181:
	s_or_b64 exec, exec, s[0:1]
	v_mov_b32_e32 v10, v0
	s_cmpk_lt_i32 s96, 0x4c0
	s_waitcnt lgkmcnt(0)
	s_barrier
	v_mov_b32_e32 v1, s101
	global_load_dword v1, v1, s[88:89] sc1
	s_waitcnt vmcnt(0)
	v_readfirstlane_b32 s98, v1
	s_cselect_b64 s[0:1], -1, 0
	s_cmpk_gt_i32 s96, 0x4bf
	v_readfirstlane_b32 s2, v10
	s_cbranch_scc1 .LBB0_183
	s_ashr_i32 s3, s96, 31
	s_lshr_b32 s3, s3, 29
	s_add_i32 s3, s96, s3
	s_ashr_i32 s4, s3, 3
	s_and_b32 s3, s3, -8
	s_sub_i32 s3, s96, s3
	s_cmp_lt_i32 s3, 0
	s_movk_i32 s5, 0x99
	s_cselect_b32 s5, s5, 0x98
	s_mul_i32 s3, s5, s3
	s_add_i32 s3, s3, s4
	s_mul_hi_i32 s4, s3, 0x6bca1af3
	s_lshr_b32 s5, s4, 31
	s_ashr_i32 s4, s4, 4
	s_add_i32 s4, s4, s5
	s_lshl_b32 s5, s4, 1
	s_mul_i32 s4, s4, 38
	s_sub_i32 s3, s3, s4
	s_bfe_u32 s4, s3, 0x10007
	s_add_i32 s4, s3, s4
	s_bfe_i32 s6, s4, 0x80000
	s_and_b32 s4, s4, 0xfe
	s_sub_i32 s3, s3, s4
	s_sext_i32_i16 s6, s6
	s_sext_i32_i8 s3, s3
	s_add_i32 s18, s5, s3
	s_ashr_i32 s4, s6, 1

; __device__ __forceinline__ unsigned xb_ld(unsigned* p)              { return __hip_atomic_load(p, __ATOMIC_RELAXED, __HIP_MEMORY_SCOPE_AGENT); }
; __device__ __forceinline__ unsigned xb_add(unsigned* p, unsigned v) { return __hip_atomic_fetch_add(p, v, __ATOMIC_RELAXED, __HIP_MEMORY_SCOPE_AGENT); }
; #define XB_SPIN(cond, bar) do { unsigned _sp = 0; while (cond) { __builtin_amdgcn_s_sleep(1); \
;     if ((++_sp & 255u) == 0u) { if (xb_ld(&(bar)[XB_TMO])) break; if (_sp > XB_SPIN_CAP) { atomicAdd(&(bar)[XB_TMO], 1u); break; } } } } while (0)
; __device__ __forceinline__ void xcd_barrier(const XcdBarrier& b) {
;     asm volatile("s_waitcnt vmcnt(0)" ::: "memory");
;     __syncthreads();
;     if (threadIdx.x == 0) {
;         unsigned* bar = b.bar;
;         __builtin_amdgcn_s_waitcnt(0);
;         unsigned nloc = b.st[0], nx = b.st[1];
;         if (nloc == 0u) { xcd_barrier_complete(bar, b.x, nloc, nx); b.st[0] = nloc; b.st[1] = nx; }
;         const unsigned old = xb_add(&bar[XB_XSUB(b.x)], 1u);
;         const unsigned gen = old / nloc;
;         asm volatile("buffer_inv sc1" ::: "memory");
;         if (old + 1u == (gen + 1u) * nloc) {
;             __builtin_amdgcn_fence(__ATOMIC_RELEASE, "agent");
;             asm volatile("s_waitcnt vmcnt(0)" ::: "memory");
;             const unsigned og = xb_add(&bar[XB_TOP], 1u);
;             const unsigned tg = og / nx;
;             if (og + 1u == (tg + 1u) * nx) xb_add(&bar[XB_TOPGEN], 1u);
;             else XB_SPIN(xb_ld(&bar[XB_TOPGEN]) == tg, bar);
;             asm volatile("" ::: "memory");
;             xb_add(&bar[XB_XGEN(b.x)], 1u);
;             asm volatile("s_waitcnt vmcnt(0)" ::: "memory");
;         } else {
;             XB_SPIN(xb_ld(&bar[XB_XGEN(b.x)]) == gen, bar);
;             asm volatile("" ::: "memory");
;             asm volatile("s_waitcnt vmcnt(0)" ::: "memory");
;         }
;     }
;     __syncthreads();
.LBB0_233:
	s_waitcnt vmcnt(0)
	s_waitcnt vmcnt(0)
	s_barrier
	s_mov_b64 s[0:1], exec
	v_readlane_b32 s2, v241, 34
	v_readlane_b32 s3, v241, 35
	s_and_b64 s[2:3], s[0:1], s[2:3]
	v_writelane_b32 v241, s94, 55
	s_nop 1
	v_writelane_b32 v241, s95, 56
	s_mov_b64 exec, s[2:3]
	s_cbranch_execz .LBB0_289
	s_waitcnt vmcnt(0) lgkmcnt(0)
	s_cmp_eq_u32 s98, 32
	s_cbranch_scc1 .Lgb_co1
	buffer_wbl2 sc1
	s_waitcnt vmcnt(0)
.Lgb_co1:
	v_mov_b32_e32 v1, s99
	v_mov_b32_e32 v2, 1
	global_atomic_add v3, v1, v2, s[88:89] sc0
	s_waitcnt vmcnt(0)
	buffer_inv sc1
	v_and_b32_e32 v4, 31, v3
	v_lshrrev_b32_e32 v3, 5, v3
	v_cmp_ne_u32_e32 vcc, 31, v4
	s_cbranch_vccnz .Lgb_wait1
	global_atomic_add v1, v2, s[88:89] offset:2048
	s_branch .Lgb_done1
.Lgb_wait1:
	s_mov_b32 s100, 0
.Lgb_spin1:
	global_load_dword v4, v1, s[88:89] offset:2048 sc1
	s_waitcnt vmcnt(0)
	v_cmp_ne_u32_e32 vcc, v4, v3
	s_cbranch_vccnz .Lgb_done1
	s_sleep 1
	s_add_i32 s100, s100, 1
	s_cmp_lt_u32 s100, 0x40000
	s_cbranch_scc1 .Lgb_spin1
.Lgb_done1:
	s_waitcnt vmcnt(0)
	s_branch .LBB0_289
	s_add_i32 s2, 0, 0x27f60
	v_mov_b32_e32 v1, s2
	s_waitcnt vmcnt(0) expcnt(0) lgkmcnt(0)
	ds_read_b32 v3, v1
	s_add_i32 s2, 0, 0x27f64
	v_mov_b32_e32 v1, s2
	ds_read_b32 v1, v1
	s_waitcnt lgkmcnt(1)
	v_cmp_ne_u32_e32 vcc, 0, v3
	s_cbranch_vccnz .LBB0_252
	v_readlane_b32 s2, v241, 0
	v_readlane_b32 s3, v241, 1
	s_load_dwordx2 s[6:7], s[2:3], 0x4
	s_add_u32 s2, s88, 0x4200
	s_addc_u32 s3, s89, 0
	s_add_u32 s4, s88, 0x4400
	s_addc_u32 s5, s89, 0
	s_waitcnt lgkmcnt(0)
	s_mul_i32 s30, s6, s93
	s_add_u32 s6, s88, 0x4500
	s_mul_i32 s30, s30, s7
	s_addc_u32 s7, s89, 0
	s_add_u32 s8, s88, 0x4600
	s_addc_u32 s9, s89, 0
	s_add_u32 s10, s88, 0x4700
	s_addc_u32 s11, s89, 0
	s_add_u32 s12, s88, 0x4800
	s_addc_u32 s13, s89, 0
	s_add_u32 s14, s88, 0x4900
	s_addc_u32 s15, s89, 0
	s_add_u32 s16, s88, 0x4a00
	s_addc_u32 s17, s89, 0
	s_add_u32 s18, s88, 0x4b00
	s_addc_u32 s19, s89, 0
	s_add_u32 s20, s88, 0x4c00
	s_addc_u32 s21, s89, 0
	s_add_u32 s22, s88, 0x4d00
	s_addc_u32 s23, s89, 0
	s_add_u32 s24, s88, 0x4e00
	s_addc_u32 s25, s89, 0
	s_add_u32 s26, s88, 0x4f00
	s_addc_u32 s27, s89, 0
	s_add_u32 s28, s88, 0x5000
	s_addc_u32 s29, s89, 0
	s_add_u32 s34, s88, 0x5100
	s_addc_u32 s35, s89, 0
	s_add_u32 s74, s88, 0x5200
	s_addc_u32 s75, s89, 0
	s_add_u32 s84, s88, 0x5300
	s_mov_b64 s[36:37], s[86:87]
	s_addc_u32 s85, s89, 0
	s_mov_b32 s31, 1
	v_mov_b32_e32 v17, 0
	s_branch .LBB0_237

; __device__ __forceinline__ unsigned xb_add(unsigned* p, unsigned v) { return __hip_atomic_fetch_add(p, v, __ATOMIC_RELAXED, __HIP_MEMORY_SCOPE_AGENT); }
; __device__ __forceinline__ void xcd_barrier(const XcdBarrier& b) {
;     asm volatile("s_waitcnt vmcnt(0)" ::: "memory");
;     __syncthreads();
;     if (threadIdx.x == 0) {
;         unsigned* bar = b.bar;
;         __builtin_amdgcn_s_waitcnt(0);
;         unsigned nloc = b.st[0], nx = b.st[1];
;         if (nloc == 0u) { xcd_barrier_complete(bar, b.x, nloc, nx); b.st[0] = nloc; b.st[1] = nx; }
;         const unsigned old = xb_add(&bar[XB_XSUB(b.x)], 1u);
;         const unsigned gen = old / nloc;
;         asm volatile("buffer_inv sc1" ::: "memory");
;         if (old + 1u == (gen + 1u) * nloc) {
.LBB0_309:
	s_waitcnt vmcnt(0)
	s_barrier
	s_mov_b64 s[2:3], exec
	v_readlane_b32 s4, v241, 34
	v_readlane_b32 s5, v241, 35
	s_and_b64 s[4:5], s[2:3], s[4:5]
	s_mov_b64 exec, s[4:5]
	s_cbranch_execz .LBB0_361
	s_waitcnt vmcnt(0) lgkmcnt(0)
	s_cmp_eq_u32 s98, 32
	s_cbranch_scc1 .Lgb_co2
	buffer_wbl2 sc1
	s_waitcnt vmcnt(0)

; __device__ __forceinline__ unsigned xb_ld(unsigned* p)              { return __hip_atomic_load(p, __ATOMIC_RELAXED, __HIP_MEMORY_SCOPE_AGENT); }
; __device__ __forceinline__ unsigned xb_add(unsigned* p, unsigned v) { return __hip_atomic_fetch_add(p, v, __ATOMIC_RELAXED, __HIP_MEMORY_SCOPE_AGENT); }
; #define XB_SPIN(cond, bar) do { unsigned _sp = 0; while (cond) { __builtin_amdgcn_s_sleep(1); \
;     if ((++_sp & 255u) == 0u) { if (xb_ld(&(bar)[XB_TMO])) break; if (_sp > XB_SPIN_CAP) { atomicAdd(&(bar)[XB_TMO], 1u); break; } } } } while (0)
; __device__ __forceinline__ void xcd_barrier(const XcdBarrier& b) {
;     ...
;             asm volatile("" ::: "memory");
;             xb_add(&bar[XB_XGEN(b.x)], 1u);
;             asm volatile("s_waitcnt vmcnt(0)" ::: "memory");
;         } else {
;             XB_SPIN(xb_ld(&bar[XB_XGEN(b.x)]) == gen, bar);
;             asm volatile("" ::: "memory");
;             asm volatile("s_waitcnt vmcnt(0)" ::: "memory");
;         }
;     }
;     __syncthreads();
.Lgb_done2:
	s_waitcnt vmcnt(0)
	s_branch .LBB0_361

; __device__ __forceinline__ unsigned xb_add(unsigned* p, unsigned v) { return __hip_atomic_fetch_add(p, v, __ATOMIC_RELAXED, __HIP_MEMORY_SCOPE_AGENT); }
; __device__ __forceinline__ void xcd_barrier(const XcdBarrier& b) {
;     asm volatile("s_waitcnt vmcnt(0)" ::: "memory");
;     __syncthreads();
;     if (threadIdx.x == 0) {
;         unsigned* bar = b.bar;
;         __builtin_amdgcn_s_waitcnt(0);
;         unsigned nloc = b.st[0], nx = b.st[1];
;         if (nloc == 0u) { xcd_barrier_complete(bar, b.x, nloc, nx); b.st[0] = nloc; b.st[1] = nx; }
;         const unsigned old = xb_add(&bar[XB_XSUB(b.x)], 1u);
;         const unsigned gen = old / nloc;
;         asm volatile("buffer_inv sc1" ::: "memory");
;         if (old + 1u == (gen + 1u) * nloc) {
.LBB0_541:
	s_waitcnt vmcnt(0)
	s_barrier
	s_mov_b64 s[2:3], exec
	v_readlane_b32 s4, v241, 34
	v_readlane_b32 s5, v241, 35
	s_and_b64 s[4:5], s[2:3], s[4:5]
	v_readlane_b32 s82, v241, 50
	v_readlane_b32 s83, v241, 51
	s_mov_b64 exec, s[4:5]
	s_cbranch_execz .LBB0_593
	s_waitcnt vmcnt(0) lgkmcnt(0)
	s_cmp_eq_u32 s98, 32
	s_cbranch_scc1 .Lgb_co3
	buffer_wbl2 sc1
	s_waitcnt vmcnt(0)

; __device__ __forceinline__ unsigned xb_add(unsigned* p, unsigned v) { return __hip_atomic_fetch_add(p, v, __ATOMIC_RELAXED, __HIP_MEMORY_SCOPE_AGENT); }
; __device__ __forceinline__ void xcd_barrier(const XcdBarrier& b) {
;     asm volatile("s_waitcnt vmcnt(0)" ::: "memory");
;     __syncthreads();
;     if (threadIdx.x == 0) {
;         unsigned* bar = b.bar;
;         __builtin_amdgcn_s_waitcnt(0);
;         unsigned nloc = b.st[0], nx = b.st[1];
;         if (nloc == 0u) { xcd_barrier_complete(bar, b.x, nloc, nx); b.st[0] = nloc; b.st[1] = nx; }
;         const unsigned old = xb_add(&bar[XB_XSUB(b.x)], 1u);
;         const unsigned gen = old / nloc;
;         asm volatile("buffer_inv sc1" ::: "memory");
;         if (old + 1u == (gen + 1u) * nloc) {
.LBB0_1242:
	s_waitcnt vmcnt(0)
	s_waitcnt lgkmcnt(0)
	s_barrier
	s_mov_b64 s[0:1], exec
	v_readlane_b32 s6, v241, 34
	v_readlane_b32 s7, v241, 35
	v_readlane_b32 s78, v241, 55
	s_and_b64 s[6:7], s[0:1], s[6:7]
	v_readlane_b32 s79, v241, 56
	s_mov_b64 exec, s[6:7]
	s_cbranch_execz .LBB0_1294
	s_waitcnt vmcnt(0) lgkmcnt(0)
	s_cmp_eq_u32 s98, 32
	s_cbranch_scc1 .Lgb_co6
	buffer_wbl2 sc1
	s_waitcnt vmcnt(0)

; __device__ __forceinline__ unsigned xb_add(unsigned* p, unsigned v) { return __hip_atomic_fetch_add(p, v, __ATOMIC_RELAXED, __HIP_MEMORY_SCOPE_AGENT); }
; __device__ __forceinline__ void xcd_barrier(const XcdBarrier& b) {
;     asm volatile("s_waitcnt vmcnt(0)" ::: "memory");
;     __syncthreads();
;     if (threadIdx.x == 0) {
;         unsigned* bar = b.bar;
;         __builtin_amdgcn_s_waitcnt(0);
;         unsigned nloc = b.st[0], nx = b.st[1];
;         if (nloc == 0u) { xcd_barrier_complete(bar, b.x, nloc, nx); b.st[0] = nloc; b.st[1] = nx; }
;         const unsigned old = xb_add(&bar[XB_XSUB(b.x)], 1u);
;         const unsigned gen = old / nloc;
;         asm volatile("buffer_inv sc1" ::: "memory");
;         if (old + 1u == (gen + 1u) * nloc) {
.LBB0_1352:
	s_waitcnt vmcnt(0)
	s_waitcnt vmcnt(0)
	s_barrier
	s_mov_b64 s[0:1], exec
	v_readlane_b32 s6, v241, 34
	v_readlane_b32 s7, v241, 35
	s_and_b64 s[6:7], s[0:1], s[6:7]
	s_mov_b64 exec, s[6:7]
	s_cbranch_execz .LBB0_1404
	s_waitcnt vmcnt(0) lgkmcnt(0)
	s_cmp_eq_u32 s98, 32
	s_cbranch_scc1 .Lgb_co7
	buffer_wbl2 sc1
	s_waitcnt vmcnt(0)

; __global__ void __launch_bounds__(NWAVES * 64, 2) skel_fwd(Args args) {
	.amdhsa_kernel _Z8skel_fwd4Args
		.amdhsa_group_segment_fixed_size 0
		.amdhsa_private_segment_fixed_size 0
		.amdhsa_kernarg_size 456
		.amdhsa_user_sgpr_count 2
		.amdhsa_user_sgpr_dispatch_ptr 0
		.amdhsa_user_sgpr_queue_ptr 0
		.amdhsa_user_sgpr_kernarg_segment_ptr 1
		.amdhsa_user_sgpr_dispatch_id 0
		.amdhsa_user_sgpr_kernarg_preload_length 0
		.amdhsa_user_sgpr_kernarg_preload_offset 0
		.amdhsa_user_sgpr_private_segment_size 0
		.amdhsa_uses_dynamic_stack 0
		.amdhsa_enable_private_segment 0
		.amdhsa_system_sgpr_workgroup_id_x 1
		.amdhsa_system_sgpr_workgroup_id_y 0
		.amdhsa_system_sgpr_workgroup_id_z 0
		.amdhsa_system_sgpr_workgroup_info 0
		.amdhsa_system_vgpr_workitem_id 0
		.amdhsa_next_free_vgpr 242
		.amdhsa_next_free_sgpr 102
		.amdhsa_accum_offset 244
		.amdhsa_reserve_vcc 1
		.amdhsa_float_round_mode_32 0
		.amdhsa_float_round_mode_16_64 0
		.amdhsa_float_denorm_mode_32 3
		.amdhsa_float_denorm_mode_16_64 3
		.amdhsa_dx10_clamp 1
		.amdhsa_ieee_mode 1
		.amdhsa_fp16_overflow 0
		.amdhsa_tg_split 0
		.amdhsa_exception_fp_ieee_invalid_op 0
		.amdhsa_exception_fp_denorm_src 0
		.amdhsa_exception_fp_ieee_div_zero 0
		.amdhsa_exception_fp_ieee_overflow 0
		.amdhsa_exception_fp_ieee_underflow 0
		.amdhsa_exception_fp_ieee_inexact 0
		.amdhsa_exception_int_div_zero 0
	.end_amdhsa_kernel

; __global__ void __launch_bounds__(NWAVES * 64, 2) skel_fwd(Args args) {
amdhsa.kernels:
  - .agpr_count:     0
    .args:
      - .offset:         0
        .size:           200
        .value_kind:     by_value
      - .offset:         200
        .size:           4
        .value_kind:     hidden_block_count_x
      - .offset:         204
        .size:           4
        .value_kind:     hidden_block_count_y
      - .offset:         208
        .size:           4
        .value_kind:     hidden_block_count_z
      - .offset:         212
        .size:           2
        .value_kind:     hidden_group_size_x
      - .offset:         214
        .size:           2
        .value_kind:     hidden_group_size_y
      - .offset:         216
        .size:           2
        .value_kind:     hidden_group_size_z
      - .offset:         218
        .size:           2
        .value_kind:     hidden_remainder_x
      - .offset:         220
        .size:           2
        .value_kind:     hidden_remainder_y
      - .offset:         222
        .size:           2
        .value_kind:     hidden_remainder_z
      - .offset:         240
        .size:           8
        .value_kind:     hidden_global_offset_x
      - .offset:         248
        .size:           8
        .value_kind:     hidden_global_offset_y
      - .offset:         256
        .size:           8
        .value_kind:     hidden_global_offset_z
      - .offset:         264
        .size:           2
        .value_kind:     hidden_grid_dims
      - .offset:         320
        .size:           4
        .value_kind:     hidden_dynamic_lds_size
    .group_segment_fixed_size: 0
    .kernarg_segment_align: 8
    .kernarg_segment_size: 456
    .language:       OpenCL C
    .language_version:
      - 2
      - 0
    .max_flat_workgroup_size: 512
    .name:           _Z8skel_fwd4Args
    .private_segment_fixed_size: 0
    .sgpr_count:     108
    .sgpr_spill_count: 85
    .symbol:         _Z8skel_fwd4Args.kd
    .uniform_work_group_size: 1
    .uses_dynamic_stack: false
    .vgpr_count:     242
    .vgpr_spill_count: 0
    .wavefront_size: 64
